# attention steady loops: the two query tiles' softmax dependency chains interleaved instruction by instruction (same operations)
# baseline (speedup 1.0000x reference)
.Ldf_itera:
	v_mfma_f32_32x32x16_bf16 v[2:17], v[170:173], v[130:133], v[114:129]
	v_mfma_f32_32x32x16_bf16 v[18:33], v[170:173], v[138:141], v[114:129]
	v_mfma_f32_32x32x16_bf16 v[2:17], v[174:177], v[134:137], v[2:17]
	v_mfma_f32_32x32x16_bf16 v[18:33], v[174:177], v[142:145], v[18:33]
	v_mul_f32_e64 v198, -v200, v205
	v_fmamk_f32 v199, v200, 0xc2000000, v198
	v_add_f32_e32 v205, 0x42000000, v205
	s_nop 7
	v_max3_f32 v206, v2, v3, v4
	v_max3_f32 v210, v18, v19, v20
	v_max3_f32 v207, v5, v6, v7
	v_max3_f32 v211, v21, v22, v23
	v_max3_f32 v208, v8, v9, v10
	v_max3_f32 v215, v24, v25, v26
	v_max3_f32 v209, v11, v12, v13
	v_max3_f32 v216, v27, v28, v29
	v_max3_f32 v206, v206, v14, v15
	v_max3_f32 v210, v210, v30, v31
	v_max3_f32 v207, v207, v16, v17
	v_max3_f32 v211, v211, v32, v33
	v_max3_f32 v206, v206, v207, v208
	v_max3_f32 v210, v210, v211, v215
	v_max_f32_e32 v206, v206, v209
	v_max_f32_e32 v210, v210, v216
	v_fma_f32 v206, v206, s98, v198
	v_fma_f32 v210, v210, s98, v199
	v_mov_b32_e32 v207, v206
	v_mov_b32_e32 v211, v210
	s_nop 1
	s_nop 1
	v_permlane32_swap_b32_e32 v206, v207
	v_permlane32_swap_b32_e32 v210, v211
	v_max3_f32 v194, v188, v206, v207
	v_max3_f32 v195, v0, v210, v211
	v_sub_f32_e32 v208, v188, v194
	v_sub_f32_e32 v215, v0, v195
	v_sub_f32_e32 v196, v198, v194
	v_sub_f32_e32 v197, v199, v195
	v_exp_f32_e32 v190, v208
	v_exp_f32_e32 v192, v215
	v_fma_f32 v2, v2, s98, v196
	v_fma_f32 v3, v3, s98, v196
	v_fma_f32 v4, v4, s98, v196
	v_fma_f32 v5, v5, s98, v196
	v_fma_f32 v6, v6, s98, v196
	v_fma_f32 v7, v7, s98, v196
	v_fma_f32 v8, v8, s98, v196
	v_fma_f32 v9, v9, s98, v196
	v_fma_f32 v10, v10, s98, v196
	v_fma_f32 v11, v11, s98, v196
	v_fma_f32 v12, v12, s98, v196
	v_fma_f32 v13, v13, s98, v196
	v_fma_f32 v14, v14, s98, v196
	v_fma_f32 v15, v15, s98, v196
	v_fma_f32 v16, v16, s98, v196
	v_fma_f32 v17, v17, s98, v196
	v_exp_f32_e32 v2, v2
	v_exp_f32_e32 v3, v3
	v_exp_f32_e32 v4, v4
	v_exp_f32_e32 v5, v5
	v_exp_f32_e32 v6, v6
	v_exp_f32_e32 v7, v7
	v_exp_f32_e32 v8, v8
	v_exp_f32_e32 v9, v9
	v_exp_f32_e32 v10, v10
	v_exp_f32_e32 v11, v11
	v_exp_f32_e32 v12, v12
	v_exp_f32_e32 v13, v13
	v_exp_f32_e32 v14, v14
	v_exp_f32_e32 v15, v15
	v_exp_f32_e32 v16, v16
	v_exp_f32_e32 v17, v17
	v_fma_f32 v18, v18, s98, v197
	v_fma_f32 v19, v19, s98, v197
	v_fma_f32 v20, v20, s98, v197
	v_fma_f32 v21, v21, s98, v197
	v_fma_f32 v22, v22, s98, v197
	v_fma_f32 v23, v23, s98, v197
	v_fma_f32 v24, v24, s98, v197
	v_fma_f32 v25, v25, s98, v197
	v_fma_f32 v26, v26, s98, v197
	v_fma_f32 v27, v27, s98, v197
	v_fma_f32 v28, v28, s98, v197
	v_fma_f32 v29, v29, s98, v197
	v_fma_f32 v30, v30, s98, v197
	v_fma_f32 v31, v31, s98, v197
	v_fma_f32 v32, v32, s98, v197
	v_fma_f32 v33, v33, s98, v197
	v_exp_f32_e32 v18, v18
	v_exp_f32_e32 v19, v19
	v_exp_f32_e32 v20, v20
	v_exp_f32_e32 v21, v21
	v_exp_f32_e32 v22, v22
	v_exp_f32_e32 v23, v23
	v_exp_f32_e32 v24, v24
	v_exp_f32_e32 v25, v25
	v_exp_f32_e32 v26, v26
	v_exp_f32_e32 v27, v27
	v_exp_f32_e32 v28, v28
	v_exp_f32_e32 v29, v29
	v_exp_f32_e32 v30, v30
	v_exp_f32_e32 v31, v31
	v_exp_f32_e32 v32, v32
	v_exp_f32_e32 v33, v33
	v_cmp_lt_f32_e32 vcc, v188, v194
	v_cmp_lt_f32_e64 s[100:101], v0, v195
	v_mov_b32_e32 v188, v194
	v_mov_b32_e32 v0, v195
	v_cvt_pk_bf16_f32 v98, v2, v3
	v_cvt_pk_bf16_f32 v106, v18, v19
	v_cvt_pk_bf16_f32 v99, v4, v5
	v_cvt_pk_bf16_f32 v107, v20, v21
	v_cvt_pk_bf16_f32 v100, v6, v7
	v_cvt_pk_bf16_f32 v108, v22, v23
	v_cvt_pk_bf16_f32 v101, v8, v9
	v_cvt_pk_bf16_f32 v109, v24, v25
	v_cvt_pk_bf16_f32 v102, v10, v11
	v_cvt_pk_bf16_f32 v110, v26, v27
	v_cvt_pk_bf16_f32 v103, v12, v13
	v_cvt_pk_bf16_f32 v111, v28, v29
	v_cvt_pk_bf16_f32 v104, v14, v15
	v_cvt_pk_bf16_f32 v112, v30, v31
	v_cvt_pk_bf16_f32 v105, v16, v17
	v_cvt_pk_bf16_f32 v113, v32, v33
	v_add_f32_e32 v206, v2, v3
	v_add_f32_e32 v210, v18, v19
	v_add_f32_e32 v207, v4, v5
	v_add_f32_e32 v211, v20, v21
	v_add_f32_e32 v208, v6, v7
	v_add_f32_e32 v215, v22, v23
	v_add_f32_e32 v209, v8, v9
	v_add_f32_e32 v216, v24, v25
	v_add_f32_e32 v206, v206, v10
	v_add_f32_e32 v210, v210, v26
	v_add_f32_e32 v207, v207, v11
	v_add_f32_e32 v211, v211, v27
	v_add_f32_e32 v208, v208, v12
	v_add_f32_e32 v215, v215, v28
	v_add_f32_e32 v209, v209, v13
	v_add_f32_e32 v216, v216, v29
	v_add_f32_e32 v206, v206, v14
	v_add_f32_e32 v210, v210, v30
	v_add_f32_e32 v207, v207, v15
	v_add_f32_e32 v211, v211, v31
	v_add_f32_e32 v208, v208, v16
	v_add_f32_e32 v215, v215, v32
	v_add_f32_e32 v209, v209, v17
	v_add_f32_e32 v216, v216, v33
	v_add_f32_e32 v206, v206, v207
	v_add_f32_e32 v210, v210, v211
	v_add_f32_e32 v208, v208, v209
	v_add_f32_e32 v215, v215, v216
	v_add_f32_e32 v206, v206, v208
	v_add_f32_e32 v210, v210, v215
	v_fmac_f32_e32 v206, v182, v190
	v_fmac_f32_e32 v210, v183, v192
	v_mov_b32_e32 v182, v206
	v_mov_b32_e32 v183, v210
	s_cbranch_vccz .Ldf_nr0a
	v_pk_mul_f32 v[82:83], v[82:83], v[190:191] op_sel_hi:[1,0]
	v_pk_mul_f32 v[84:85], v[84:85], v[190:191] op_sel_hi:[1,0]
	v_pk_mul_f32 v[86:87], v[86:87], v[190:191] op_sel_hi:[1,0]
	v_pk_mul_f32 v[88:89], v[88:89], v[190:191] op_sel_hi:[1,0]
	v_pk_mul_f32 v[90:91], v[90:91], v[190:191] op_sel_hi:[1,0]
	v_pk_mul_f32 v[92:93], v[92:93], v[190:191] op_sel_hi:[1,0]
	v_pk_mul_f32 v[94:95], v[94:95], v[190:191] op_sel_hi:[1,0]
	v_pk_mul_f32 v[96:97], v[96:97], v[190:191] op_sel_hi:[1,0]
	v_pk_mul_f32 v[66:67], v[66:67], v[190:191] op_sel_hi:[1,0]
	v_pk_mul_f32 v[68:69], v[68:69], v[190:191] op_sel_hi:[1,0]
	v_pk_mul_f32 v[70:71], v[70:71], v[190:191] op_sel_hi:[1,0]
	v_pk_mul_f32 v[72:73], v[72:73], v[190:191] op_sel_hi:[1,0]
	v_pk_mul_f32 v[74:75], v[74:75], v[190:191] op_sel_hi:[1,0]
	v_pk_mul_f32 v[76:77], v[76:77], v[190:191] op_sel_hi:[1,0]
	v_pk_mul_f32 v[78:79], v[78:79], v[190:191] op_sel_hi:[1,0]
	v_pk_mul_f32 v[80:81], v[80:81], v[190:191] op_sel_hi:[1,0]
	s_nop 1
.Ldf_nr0a:
	s_waitcnt vmcnt(2)
	v_mfma_f32_32x32x16_bf16 v[82:97], v[166:169], v[98:101], v[82:97]
	v_mfma_f32_32x32x16_bf16 v[66:81], v[158:161], v[98:101], v[66:81]
	v_mfma_f32_32x32x16_bf16 v[82:97], v[162:165], v[102:105], v[82:97]
	v_mfma_f32_32x32x16_bf16 v[66:81], v[154:157], v[102:105], v[66:81]
	s_cmp_lg_u64 s[100:101], 0
	s_cbranch_scc0 .Ldf_nr1a
	v_pk_mul_f32 v[50:51], v[50:51], v[192:193] op_sel_hi:[1,0]
	v_pk_mul_f32 v[52:53], v[52:53], v[192:193] op_sel_hi:[1,0]
	v_pk_mul_f32 v[54:55], v[54:55], v[192:193] op_sel_hi:[1,0]
	v_pk_mul_f32 v[56:57], v[56:57], v[192:193] op_sel_hi:[1,0]
	v_pk_mul_f32 v[58:59], v[58:59], v[192:193] op_sel_hi:[1,0]
	v_pk_mul_f32 v[60:61], v[60:61], v[192:193] op_sel_hi:[1,0]
	v_pk_mul_f32 v[62:63], v[62:63], v[192:193] op_sel_hi:[1,0]
	v_pk_mul_f32 v[64:65], v[64:65], v[192:193] op_sel_hi:[1,0]
	v_pk_mul_f32 v[34:35], v[34:35], v[192:193] op_sel_hi:[1,0]
	v_pk_mul_f32 v[36:37], v[36:37], v[192:193] op_sel_hi:[1,0]
	v_pk_mul_f32 v[38:39], v[38:39], v[192:193] op_sel_hi:[1,0]
	v_pk_mul_f32 v[40:41], v[40:41], v[192:193] op_sel_hi:[1,0]
	v_pk_mul_f32 v[42:43], v[42:43], v[192:193] op_sel_hi:[1,0]
	v_pk_mul_f32 v[44:45], v[44:45], v[192:193] op_sel_hi:[1,0]
	v_pk_mul_f32 v[46:47], v[46:47], v[192:193] op_sel_hi:[1,0]
	v_pk_mul_f32 v[48:49], v[48:49], v[192:193] op_sel_hi:[1,0]
	s_nop 1

.Ldf_iterb:
	v_mfma_f32_32x32x16_bf16 v[2:17], v[146:149], v[130:133], v[114:129]
	v_mfma_f32_32x32x16_bf16 v[18:33], v[146:149], v[138:141], v[114:129]
	v_mfma_f32_32x32x16_bf16 v[2:17], v[150:153], v[134:137], v[2:17]
	v_mfma_f32_32x32x16_bf16 v[18:33], v[150:153], v[142:145], v[18:33]
	v_mul_f32_e64 v198, -v200, v205
	v_fmamk_f32 v199, v200, 0xc2000000, v198
	v_add_f32_e32 v205, 0x42000000, v205
	s_nop 7
	v_max3_f32 v206, v2, v3, v4
	v_max3_f32 v210, v18, v19, v20
	v_max3_f32 v207, v5, v6, v7
	v_max3_f32 v211, v21, v22, v23
	v_max3_f32 v208, v8, v9, v10
	v_max3_f32 v215, v24, v25, v26
	v_max3_f32 v209, v11, v12, v13
	v_max3_f32 v216, v27, v28, v29
	v_max3_f32 v206, v206, v14, v15
	v_max3_f32 v210, v210, v30, v31
	v_max3_f32 v207, v207, v16, v17
	v_max3_f32 v211, v211, v32, v33
	v_max3_f32 v206, v206, v207, v208
	v_max3_f32 v210, v210, v211, v215
	v_max_f32_e32 v206, v206, v209
	v_max_f32_e32 v210, v210, v216
	v_fma_f32 v206, v206, s98, v198
	v_fma_f32 v210, v210, s98, v199
	v_mov_b32_e32 v207, v206
	v_mov_b32_e32 v211, v210
	s_nop 1
	s_nop 1
	v_permlane32_swap_b32_e32 v206, v207
	v_permlane32_swap_b32_e32 v210, v211
	v_max3_f32 v194, v188, v206, v207
	v_max3_f32 v195, v0, v210, v211
	v_sub_f32_e32 v208, v188, v194
	v_sub_f32_e32 v215, v0, v195
	v_sub_f32_e32 v196, v198, v194
	v_sub_f32_e32 v197, v199, v195
	v_exp_f32_e32 v190, v208
	v_exp_f32_e32 v192, v215
	v_fma_f32 v2, v2, s98, v196
	v_fma_f32 v3, v3, s98, v196
	v_fma_f32 v4, v4, s98, v196
	v_fma_f32 v5, v5, s98, v196
	v_fma_f32 v6, v6, s98, v196
	v_fma_f32 v7, v7, s98, v196
	v_fma_f32 v8, v8, s98, v196
	v_fma_f32 v9, v9, s98, v196
	v_fma_f32 v10, v10, s98, v196
	v_fma_f32 v11, v11, s98, v196
	v_fma_f32 v12, v12, s98, v196
	v_fma_f32 v13, v13, s98, v196
	v_fma_f32 v14, v14, s98, v196
	v_fma_f32 v15, v15, s98, v196
	v_fma_f32 v16, v16, s98, v196
	v_fma_f32 v17, v17, s98, v196
	v_exp_f32_e32 v2, v2
	v_exp_f32_e32 v3, v3
	v_exp_f32_e32 v4, v4
	v_exp_f32_e32 v5, v5
	v_exp_f32_e32 v6, v6
	v_exp_f32_e32 v7, v7
	v_exp_f32_e32 v8, v8
	v_exp_f32_e32 v9, v9
	v_exp_f32_e32 v10, v10
	v_exp_f32_e32 v11, v11
	v_exp_f32_e32 v12, v12
	v_exp_f32_e32 v13, v13
	v_exp_f32_e32 v14, v14
	v_exp_f32_e32 v15, v15
	v_exp_f32_e32 v16, v16
	v_exp_f32_e32 v17, v17
	v_fma_f32 v18, v18, s98, v197
	v_fma_f32 v19, v19, s98, v197
	v_fma_f32 v20, v20, s98, v197
	v_fma_f32 v21, v21, s98, v197
	v_fma_f32 v22, v22, s98, v197
	v_fma_f32 v23, v23, s98, v197
	v_fma_f32 v24, v24, s98, v197
	v_fma_f32 v25, v25, s98, v197
	v_fma_f32 v26, v26, s98, v197
	v_fma_f32 v27, v27, s98, v197
	v_fma_f32 v28, v28, s98, v197
	v_fma_f32 v29, v29, s98, v197
	v_fma_f32 v30, v30, s98, v197
	v_fma_f32 v31, v31, s98, v197
	v_fma_f32 v32, v32, s98, v197
	v_fma_f32 v33, v33, s98, v197
	v_exp_f32_e32 v18, v18
	v_exp_f32_e32 v19, v19
	v_exp_f32_e32 v20, v20
	v_exp_f32_e32 v21, v21
	v_exp_f32_e32 v22, v22
	v_exp_f32_e32 v23, v23
	v_exp_f32_e32 v24, v24
	v_exp_f32_e32 v25, v25
	v_exp_f32_e32 v26, v26
	v_exp_f32_e32 v27, v27
	v_exp_f32_e32 v28, v28
	v_exp_f32_e32 v29, v29
	v_exp_f32_e32 v30, v30
	v_exp_f32_e32 v31, v31
	v_exp_f32_e32 v32, v32
	v_exp_f32_e32 v33, v33
	v_cmp_lt_f32_e32 vcc, v188, v194
	v_cmp_lt_f32_e64 s[100:101], v0, v195
	v_mov_b32_e32 v188, v194
	v_mov_b32_e32 v0, v195
	v_cvt_pk_bf16_f32 v98, v2, v3
	v_cvt_pk_bf16_f32 v106, v18, v19
	v_cvt_pk_bf16_f32 v99, v4, v5
	v_cvt_pk_bf16_f32 v107, v20, v21
	v_cvt_pk_bf16_f32 v100, v6, v7
	v_cvt_pk_bf16_f32 v108, v22, v23
	v_cvt_pk_bf16_f32 v101, v8, v9
	v_cvt_pk_bf16_f32 v109, v24, v25
	v_cvt_pk_bf16_f32 v102, v10, v11
	v_cvt_pk_bf16_f32 v110, v26, v27
	v_cvt_pk_bf16_f32 v103, v12, v13
	v_cvt_pk_bf16_f32 v111, v28, v29
	v_cvt_pk_bf16_f32 v104, v14, v15
	v_cvt_pk_bf16_f32 v112, v30, v31
	v_cvt_pk_bf16_f32 v105, v16, v17
	v_cvt_pk_bf16_f32 v113, v32, v33
	v_add_f32_e32 v206, v2, v3
	v_add_f32_e32 v210, v18, v19
	v_add_f32_e32 v207, v4, v5
	v_add_f32_e32 v211, v20, v21
	v_add_f32_e32 v208, v6, v7
	v_add_f32_e32 v215, v22, v23
	v_add_f32_e32 v209, v8, v9
	v_add_f32_e32 v216, v24, v25
	v_add_f32_e32 v206, v206, v10
	v_add_f32_e32 v210, v210, v26
	v_add_f32_e32 v207, v207, v11
	v_add_f32_e32 v211, v211, v27
	v_add_f32_e32 v208, v208, v12
	v_add_f32_e32 v215, v215, v28
	v_add_f32_e32 v209, v209, v13
	v_add_f32_e32 v216, v216, v29
	v_add_f32_e32 v206, v206, v14
	v_add_f32_e32 v210, v210, v30
	v_add_f32_e32 v207, v207, v15
	v_add_f32_e32 v211, v211, v31
	v_add_f32_e32 v208, v208, v16
	v_add_f32_e32 v215, v215, v32
	v_add_f32_e32 v209, v209, v17
	v_add_f32_e32 v216, v216, v33
	v_add_f32_e32 v206, v206, v207
	v_add_f32_e32 v210, v210, v211
	v_add_f32_e32 v208, v208, v209
	v_add_f32_e32 v215, v215, v216
	v_add_f32_e32 v206, v206, v208
	v_add_f32_e32 v210, v210, v215
	v_fmac_f32_e32 v206, v182, v190
	v_fmac_f32_e32 v210, v183, v192
	v_mov_b32_e32 v182, v206
	v_mov_b32_e32 v183, v210
	s_cbranch_vccz .Ldf_nr0b
	v_pk_mul_f32 v[82:83], v[82:83], v[190:191] op_sel_hi:[1,0]
	v_pk_mul_f32 v[84:85], v[84:85], v[190:191] op_sel_hi:[1,0]
	v_pk_mul_f32 v[86:87], v[86:87], v[190:191] op_sel_hi:[1,0]
	v_pk_mul_f32 v[88:89], v[88:89], v[190:191] op_sel_hi:[1,0]
	v_pk_mul_f32 v[90:91], v[90:91], v[190:191] op_sel_hi:[1,0]
	v_pk_mul_f32 v[92:93], v[92:93], v[190:191] op_sel_hi:[1,0]
	v_pk_mul_f32 v[94:95], v[94:95], v[190:191] op_sel_hi:[1,0]
	v_pk_mul_f32 v[96:97], v[96:97], v[190:191] op_sel_hi:[1,0]
	v_pk_mul_f32 v[66:67], v[66:67], v[190:191] op_sel_hi:[1,0]
	v_pk_mul_f32 v[68:69], v[68:69], v[190:191] op_sel_hi:[1,0]
	v_pk_mul_f32 v[70:71], v[70:71], v[190:191] op_sel_hi:[1,0]
	v_pk_mul_f32 v[72:73], v[72:73], v[190:191] op_sel_hi:[1,0]
	v_pk_mul_f32 v[74:75], v[74:75], v[190:191] op_sel_hi:[1,0]
	v_pk_mul_f32 v[76:77], v[76:77], v[190:191] op_sel_hi:[1,0]
	v_pk_mul_f32 v[78:79], v[78:79], v[190:191] op_sel_hi:[1,0]
	v_pk_mul_f32 v[80:81], v[80:81], v[190:191] op_sel_hi:[1,0]
	s_nop 1

.Lfx_itera:
	s_waitcnt lgkmcnt(0)
	v_mfma_f32_32x32x16_bf16 v[2:17], v[206:209], v[130:133], v[114:129]
	v_mfma_f32_32x32x16_bf16 v[18:33], v[206:209], v[146:149], v[114:129]
	v_mfma_f32_32x32x16_bf16 v[2:17], v[202:205], v[134:137], v[2:17]
	v_mfma_f32_32x32x16_bf16 v[18:33], v[202:205], v[150:153], v[18:33]
	v_mfma_f32_32x32x16_bf16 v[2:17], v[198:201], v[138:141], v[2:17]
	v_mfma_f32_32x32x16_bf16 v[18:33], v[198:201], v[154:157], v[18:33]
	v_mfma_f32_32x32x16_bf16 v[2:17], v[194:197], v[142:145], v[2:17]
	v_mfma_f32_32x32x16_bf16 v[18:33], v[194:197], v[158:161], v[18:33]
	s_nop 10
	v_max3_f32 v230, v2, v3, v4
	v_max3_f32 v222, v18, v19, v20
	v_max3_f32 v231, v5, v6, v7
	v_max3_f32 v223, v21, v22, v23
	v_max3_f32 v232, v8, v9, v10
	v_max3_f32 v234, v24, v25, v26
	v_max3_f32 v233, v11, v12, v13
	v_max3_f32 v235, v27, v28, v29
	v_max3_f32 v230, v230, v14, v15
	v_max3_f32 v222, v222, v30, v31
	v_max3_f32 v231, v231, v16, v17
	v_max3_f32 v223, v223, v32, v33
	v_max3_f32 v230, v230, v231, v232
	v_max3_f32 v222, v222, v223, v234
	v_max_f32_e32 v230, v230, v233
	v_max_f32_e32 v222, v222, v235
	v_mul_f32_e32 v230, s98, v230
	v_mul_f32_e32 v222, s98, v222
	v_mov_b32_e32 v231, v230
	v_mov_b32_e32 v223, v222
	s_nop 1
	s_nop 1
	v_permlane32_swap_b32_e32 v230, v231
	v_permlane32_swap_b32_e32 v222, v223
	v_max3_f32 v220, v224, v230, v231
	v_max3_f32 v221, v225, v222, v223
	v_sub_f32_e32 v232, v224, v220
	v_sub_f32_e32 v234, v225, v221
	v_exp_f32_e32 v226, v232
	v_exp_f32_e32 v228, v234
	v_fma_f32 v2, v2, s98, -v220
	v_fma_f32 v3, v3, s98, -v220
	v_fma_f32 v4, v4, s98, -v220
	v_fma_f32 v5, v5, s98, -v220
	v_fma_f32 v6, v6, s98, -v220
	v_fma_f32 v7, v7, s98, -v220
	v_fma_f32 v8, v8, s98, -v220
	v_fma_f32 v9, v9, s98, -v220
	v_fma_f32 v10, v10, s98, -v220
	v_fma_f32 v11, v11, s98, -v220
	v_fma_f32 v12, v12, s98, -v220
	v_fma_f32 v13, v13, s98, -v220
	v_fma_f32 v14, v14, s98, -v220
	v_fma_f32 v15, v15, s98, -v220
	v_fma_f32 v16, v16, s98, -v220
	v_fma_f32 v17, v17, s98, -v220
	v_exp_f32_e32 v2, v2
	v_exp_f32_e32 v3, v3
	v_exp_f32_e32 v4, v4
	v_exp_f32_e32 v5, v5
	v_exp_f32_e32 v6, v6
	v_exp_f32_e32 v7, v7
	v_exp_f32_e32 v8, v8
	v_exp_f32_e32 v9, v9
	v_exp_f32_e32 v10, v10
	v_exp_f32_e32 v11, v11
	v_exp_f32_e32 v12, v12
	v_exp_f32_e32 v13, v13
	v_exp_f32_e32 v14, v14
	v_exp_f32_e32 v15, v15
	v_exp_f32_e32 v16, v16
	v_exp_f32_e32 v17, v17
	v_fma_f32 v18, v18, s98, -v221
	v_fma_f32 v19, v19, s98, -v221
	v_fma_f32 v20, v20, s98, -v221
	v_fma_f32 v21, v21, s98, -v221
	v_fma_f32 v22, v22, s98, -v221
	v_fma_f32 v23, v23, s98, -v221
	v_fma_f32 v24, v24, s98, -v221
	v_fma_f32 v25, v25, s98, -v221
	v_fma_f32 v26, v26, s98, -v221
	v_fma_f32 v27, v27, s98, -v221
	v_fma_f32 v28, v28, s98, -v221
	v_fma_f32 v29, v29, s98, -v221
	v_fma_f32 v30, v30, s98, -v221
	v_fma_f32 v31, v31, s98, -v221
	v_fma_f32 v32, v32, s98, -v221
	v_fma_f32 v33, v33, s98, -v221
	v_exp_f32_e32 v18, v18
	v_exp_f32_e32 v19, v19
	v_exp_f32_e32 v20, v20
	v_exp_f32_e32 v21, v21
	v_exp_f32_e32 v22, v22
	v_exp_f32_e32 v23, v23
	v_exp_f32_e32 v24, v24
	v_exp_f32_e32 v25, v25
	v_exp_f32_e32 v26, v26
	v_exp_f32_e32 v27, v27
	v_exp_f32_e32 v28, v28
	v_exp_f32_e32 v29, v29
	v_exp_f32_e32 v30, v30
	v_exp_f32_e32 v31, v31
	v_exp_f32_e32 v32, v32
	v_exp_f32_e32 v33, v33
	v_cmp_lt_f32_e32 vcc, v224, v220
	v_cmp_lt_f32_e64 s[100:101], v225, v221
	v_mov_b32_e32 v224, v220
	v_mov_b32_e32 v225, v221
	v_cvt_pk_bf16_f32 v98, v2, v3
	v_cvt_pk_bf16_f32 v106, v18, v19
	v_cvt_pk_bf16_f32 v99, v4, v5
	v_cvt_pk_bf16_f32 v107, v20, v21
	v_cvt_pk_bf16_f32 v100, v6, v7
	v_cvt_pk_bf16_f32 v108, v22, v23
	v_cvt_pk_bf16_f32 v101, v8, v9
	v_cvt_pk_bf16_f32 v109, v24, v25
	v_cvt_pk_bf16_f32 v102, v10, v11
	v_cvt_pk_bf16_f32 v110, v26, v27
	v_cvt_pk_bf16_f32 v103, v12, v13
	v_cvt_pk_bf16_f32 v111, v28, v29
	v_cvt_pk_bf16_f32 v104, v14, v15
	v_cvt_pk_bf16_f32 v112, v30, v31
	v_cvt_pk_bf16_f32 v105, v16, v17
	v_cvt_pk_bf16_f32 v113, v32, v33
	v_add_f32_e32 v230, v2, v3
	v_add_f32_e32 v222, v18, v19
	v_add_f32_e32 v231, v4, v5
	v_add_f32_e32 v223, v20, v21
	v_add_f32_e32 v232, v6, v7
	v_add_f32_e32 v234, v22, v23
	v_add_f32_e32 v233, v8, v9
	v_add_f32_e32 v235, v24, v25
	v_add_f32_e32 v230, v230, v10
	v_add_f32_e32 v222, v222, v26
	v_add_f32_e32 v231, v231, v11
	v_add_f32_e32 v223, v223, v27
	v_add_f32_e32 v232, v232, v12
	v_add_f32_e32 v234, v234, v28
	v_add_f32_e32 v233, v233, v13
	v_add_f32_e32 v235, v235, v29
	v_add_f32_e32 v230, v230, v14
	v_add_f32_e32 v222, v222, v30
	v_add_f32_e32 v231, v231, v15
	v_add_f32_e32 v223, v223, v31
	v_add_f32_e32 v232, v232, v16
	v_add_f32_e32 v234, v234, v32
	v_add_f32_e32 v233, v233, v17
	v_add_f32_e32 v235, v235, v33
	v_add_f32_e32 v230, v230, v231
	v_add_f32_e32 v222, v222, v223
	v_add_f32_e32 v232, v232, v233
	v_add_f32_e32 v234, v234, v235
	v_add_f32_e32 v230, v230, v232
	v_add_f32_e32 v222, v222, v234
	v_fmac_f32_e32 v230, v218, v226
	v_fmac_f32_e32 v222, v219, v228
	v_mov_b32_e32 v218, v230
	v_mov_b32_e32 v219, v222
	s_cbranch_vccz .Lfx_nr0a
	v_pk_mul_f32 v[82:83], v[82:83], v[226:227] op_sel_hi:[1,0]
	v_pk_mul_f32 v[84:85], v[84:85], v[226:227] op_sel_hi:[1,0]
	v_pk_mul_f32 v[86:87], v[86:87], v[226:227] op_sel_hi:[1,0]
	v_pk_mul_f32 v[88:89], v[88:89], v[226:227] op_sel_hi:[1,0]
	v_pk_mul_f32 v[90:91], v[90:91], v[226:227] op_sel_hi:[1,0]
	v_pk_mul_f32 v[92:93], v[92:93], v[226:227] op_sel_hi:[1,0]
	v_pk_mul_f32 v[94:95], v[94:95], v[226:227] op_sel_hi:[1,0]
	v_pk_mul_f32 v[96:97], v[96:97], v[226:227] op_sel_hi:[1,0]
	v_pk_mul_f32 v[66:67], v[66:67], v[226:227] op_sel_hi:[1,0]
	v_pk_mul_f32 v[68:69], v[68:69], v[226:227] op_sel_hi:[1,0]
	v_pk_mul_f32 v[70:71], v[70:71], v[226:227] op_sel_hi:[1,0]
	v_pk_mul_f32 v[72:73], v[72:73], v[226:227] op_sel_hi:[1,0]
	v_pk_mul_f32 v[74:75], v[74:75], v[226:227] op_sel_hi:[1,0]
	v_pk_mul_f32 v[76:77], v[76:77], v[226:227] op_sel_hi:[1,0]
	v_pk_mul_f32 v[78:79], v[78:79], v[226:227] op_sel_hi:[1,0]
	v_pk_mul_f32 v[80:81], v[80:81], v[226:227] op_sel_hi:[1,0]
	s_nop 1
.Lfx_nr0a:
	s_waitcnt vmcnt(4)
	v_mfma_f32_32x32x16_bf16 v[82:97], v[190:193], v[98:101], v[82:97]
	v_mfma_f32_32x32x16_bf16 v[66:81], v[182:185], v[98:101], v[66:81]
	v_mfma_f32_32x32x16_bf16 v[82:97], v[186:189], v[102:105], v[82:97]
	v_mfma_f32_32x32x16_bf16 v[66:81], v[178:181], v[102:105], v[66:81]
	s_cmp_lg_u64 s[100:101], 0
	s_cbranch_scc0 .Lfx_nr1a
	v_pk_mul_f32 v[50:51], v[50:51], v[228:229] op_sel_hi:[1,0]
	v_pk_mul_f32 v[52:53], v[52:53], v[228:229] op_sel_hi:[1,0]
	v_pk_mul_f32 v[54:55], v[54:55], v[228:229] op_sel_hi:[1,0]
	v_pk_mul_f32 v[56:57], v[56:57], v[228:229] op_sel_hi:[1,0]
	v_pk_mul_f32 v[58:59], v[58:59], v[228:229] op_sel_hi:[1,0]
	v_pk_mul_f32 v[60:61], v[60:61], v[228:229] op_sel_hi:[1,0]
	v_pk_mul_f32 v[62:63], v[62:63], v[228:229] op_sel_hi:[1,0]
	v_pk_mul_f32 v[64:65], v[64:65], v[228:229] op_sel_hi:[1,0]
	v_pk_mul_f32 v[34:35], v[34:35], v[228:229] op_sel_hi:[1,0]
	v_pk_mul_f32 v[36:37], v[36:37], v[228:229] op_sel_hi:[1,0]
	v_pk_mul_f32 v[38:39], v[38:39], v[228:229] op_sel_hi:[1,0]
	v_pk_mul_f32 v[40:41], v[40:41], v[228:229] op_sel_hi:[1,0]
	v_pk_mul_f32 v[42:43], v[42:43], v[228:229] op_sel_hi:[1,0]
	v_pk_mul_f32 v[44:45], v[44:45], v[228:229] op_sel_hi:[1,0]
	v_pk_mul_f32 v[46:47], v[46:47], v[228:229] op_sel_hi:[1,0]
	v_pk_mul_f32 v[48:49], v[48:49], v[228:229] op_sel_hi:[1,0]
	s_nop 1

.Lfx_iterb:
	s_waitcnt lgkmcnt(0)
	v_mfma_f32_32x32x16_bf16 v[2:17], v[174:177], v[130:133], v[114:129]
	v_mfma_f32_32x32x16_bf16 v[18:33], v[174:177], v[146:149], v[114:129]
	v_mfma_f32_32x32x16_bf16 v[2:17], v[170:173], v[134:137], v[2:17]
	v_mfma_f32_32x32x16_bf16 v[18:33], v[170:173], v[150:153], v[18:33]
	v_mfma_f32_32x32x16_bf16 v[2:17], v[166:169], v[138:141], v[2:17]
	v_mfma_f32_32x32x16_bf16 v[18:33], v[166:169], v[154:157], v[18:33]
	v_mfma_f32_32x32x16_bf16 v[2:17], v[162:165], v[142:145], v[2:17]
	v_mfma_f32_32x32x16_bf16 v[18:33], v[162:165], v[158:161], v[18:33]
	s_nop 10
	v_max3_f32 v230, v2, v3, v4
	v_max3_f32 v222, v18, v19, v20
	v_max3_f32 v231, v5, v6, v7
	v_max3_f32 v223, v21, v22, v23
	v_max3_f32 v232, v8, v9, v10
	v_max3_f32 v234, v24, v25, v26
	v_max3_f32 v233, v11, v12, v13
	v_max3_f32 v235, v27, v28, v29
	v_max3_f32 v230, v230, v14, v15
	v_max3_f32 v222, v222, v30, v31
	v_max3_f32 v231, v231, v16, v17
	v_max3_f32 v223, v223, v32, v33
	v_max3_f32 v230, v230, v231, v232
	v_max3_f32 v222, v222, v223, v234
	v_max_f32_e32 v230, v230, v233
	v_max_f32_e32 v222, v222, v235
	v_mul_f32_e32 v230, s98, v230
	v_mul_f32_e32 v222, s98, v222
	v_mov_b32_e32 v231, v230
	v_mov_b32_e32 v223, v222
	s_nop 1
	s_nop 1
	v_permlane32_swap_b32_e32 v230, v231
	v_permlane32_swap_b32_e32 v222, v223
	v_max3_f32 v220, v224, v230, v231
	v_max3_f32 v221, v225, v222, v223
	v_sub_f32_e32 v232, v224, v220
	v_sub_f32_e32 v234, v225, v221
	v_exp_f32_e32 v226, v232
	v_exp_f32_e32 v228, v234
	v_fma_f32 v2, v2, s98, -v220
	v_fma_f32 v3, v3, s98, -v220
	v_fma_f32 v4, v4, s98, -v220
	v_fma_f32 v5, v5, s98, -v220
	v_fma_f32 v6, v6, s98, -v220
	v_fma_f32 v7, v7, s98, -v220
	v_fma_f32 v8, v8, s98, -v220
	v_fma_f32 v9, v9, s98, -v220
	v_fma_f32 v10, v10, s98, -v220
	v_fma_f32 v11, v11, s98, -v220
	v_fma_f32 v12, v12, s98, -v220
	v_fma_f32 v13, v13, s98, -v220
	v_fma_f32 v14, v14, s98, -v220
	v_fma_f32 v15, v15, s98, -v220
	v_fma_f32 v16, v16, s98, -v220
	v_fma_f32 v17, v17, s98, -v220
	v_exp_f32_e32 v2, v2
	v_exp_f32_e32 v3, v3
	v_exp_f32_e32 v4, v4
	v_exp_f32_e32 v5, v5
	v_exp_f32_e32 v6, v6
	v_exp_f32_e32 v7, v7
	v_exp_f32_e32 v8, v8
	v_exp_f32_e32 v9, v9
	v_exp_f32_e32 v10, v10
	v_exp_f32_e32 v11, v11
	v_exp_f32_e32 v12, v12
	v_exp_f32_e32 v13, v13
	v_exp_f32_e32 v14, v14
	v_exp_f32_e32 v15, v15
	v_exp_f32_e32 v16, v16
	v_exp_f32_e32 v17, v17
	v_fma_f32 v18, v18, s98, -v221
	v_fma_f32 v19, v19, s98, -v221
	v_fma_f32 v20, v20, s98, -v221
	v_fma_f32 v21, v21, s98, -v221
	v_fma_f32 v22, v22, s98, -v221
	v_fma_f32 v23, v23, s98, -v221
	v_fma_f32 v24, v24, s98, -v221
	v_fma_f32 v25, v25, s98, -v221
	v_fma_f32 v26, v26, s98, -v221
	v_fma_f32 v27, v27, s98, -v221
	v_fma_f32 v28, v28, s98, -v221
	v_fma_f32 v29, v29, s98, -v221
	v_fma_f32 v30, v30, s98, -v221
	v_fma_f32 v31, v31, s98, -v221
	v_fma_f32 v32, v32, s98, -v221
	v_fma_f32 v33, v33, s98, -v221
	v_exp_f32_e32 v18, v18
	v_exp_f32_e32 v19, v19
	v_exp_f32_e32 v20, v20
	v_exp_f32_e32 v21, v21
	v_exp_f32_e32 v22, v22
	v_exp_f32_e32 v23, v23
	v_exp_f32_e32 v24, v24
	v_exp_f32_e32 v25, v25
	v_exp_f32_e32 v26, v26
	v_exp_f32_e32 v27, v27
	v_exp_f32_e32 v28, v28
	v_exp_f32_e32 v29, v29
	v_exp_f32_e32 v30, v30
	v_exp_f32_e32 v31, v31
	v_exp_f32_e32 v32, v32
	v_exp_f32_e32 v33, v33
	v_cmp_lt_f32_e32 vcc, v224, v220
	v_cmp_lt_f32_e64 s[100:101], v225, v221
	v_mov_b32_e32 v224, v220
	v_mov_b32_e32 v225, v221
	v_cvt_pk_bf16_f32 v98, v2, v3
	v_cvt_pk_bf16_f32 v106, v18, v19
	v_cvt_pk_bf16_f32 v99, v4, v5
	v_cvt_pk_bf16_f32 v107, v20, v21
	v_cvt_pk_bf16_f32 v100, v6, v7
	v_cvt_pk_bf16_f32 v108, v22, v23
	v_cvt_pk_bf16_f32 v101, v8, v9
	v_cvt_pk_bf16_f32 v109, v24, v25
	v_cvt_pk_bf16_f32 v102, v10, v11
	v_cvt_pk_bf16_f32 v110, v26, v27
	v_cvt_pk_bf16_f32 v103, v12, v13
	v_cvt_pk_bf16_f32 v111, v28, v29
	v_cvt_pk_bf16_f32 v104, v14, v15
	v_cvt_pk_bf16_f32 v112, v30, v31
	v_cvt_pk_bf16_f32 v105, v16, v17
	v_cvt_pk_bf16_f32 v113, v32, v33
	v_add_f32_e32 v230, v2, v3
	v_add_f32_e32 v222, v18, v19
	v_add_f32_e32 v231, v4, v5
	v_add_f32_e32 v223, v20, v21
	v_add_f32_e32 v232, v6, v7
	v_add_f32_e32 v234, v22, v23
	v_add_f32_e32 v233, v8, v9
	v_add_f32_e32 v235, v24, v25
	v_add_f32_e32 v230, v230, v10
	v_add_f32_e32 v222, v222, v26
	v_add_f32_e32 v231, v231, v11
	v_add_f32_e32 v223, v223, v27
	v_add_f32_e32 v232, v232, v12
	v_add_f32_e32 v234, v234, v28
	v_add_f32_e32 v233, v233, v13
	v_add_f32_e32 v235, v235, v29
	v_add_f32_e32 v230, v230, v14
	v_add_f32_e32 v222, v222, v30
	v_add_f32_e32 v231, v231, v15
	v_add_f32_e32 v223, v223, v31
	v_add_f32_e32 v232, v232, v16
	v_add_f32_e32 v234, v234, v32
	v_add_f32_e32 v233, v233, v17
	v_add_f32_e32 v235, v235, v33
	v_add_f32_e32 v230, v230, v231
	v_add_f32_e32 v222, v222, v223
	v_add_f32_e32 v232, v232, v233
	v_add_f32_e32 v234, v234, v235
	v_add_f32_e32 v230, v230, v232
	v_add_f32_e32 v222, v222, v234
	v_fmac_f32_e32 v230, v218, v226
	v_fmac_f32_e32 v222, v219, v228
	v_mov_b32_e32 v218, v230
	v_mov_b32_e32 v219, v222
	s_cbranch_vccz .Lfx_nr0b
	v_pk_mul_f32 v[82:83], v[82:83], v[226:227] op_sel_hi:[1,0]
	v_pk_mul_f32 v[84:85], v[84:85], v[226:227] op_sel_hi:[1,0]
	v_pk_mul_f32 v[86:87], v[86:87], v[226:227] op_sel_hi:[1,0]
	v_pk_mul_f32 v[88:89], v[88:89], v[226:227] op_sel_hi:[1,0]
	v_pk_mul_f32 v[90:91], v[90:91], v[226:227] op_sel_hi:[1,0]
	v_pk_mul_f32 v[92:93], v[92:93], v[226:227] op_sel_hi:[1,0]
	v_pk_mul_f32 v[94:95], v[94:95], v[226:227] op_sel_hi:[1,0]
	v_pk_mul_f32 v[96:97], v[96:97], v[226:227] op_sel_hi:[1,0]
	v_pk_mul_f32 v[66:67], v[66:67], v[226:227] op_sel_hi:[1,0]
	v_pk_mul_f32 v[68:69], v[68:69], v[226:227] op_sel_hi:[1,0]
	v_pk_mul_f32 v[70:71], v[70:71], v[226:227] op_sel_hi:[1,0]
	v_pk_mul_f32 v[72:73], v[72:73], v[226:227] op_sel_hi:[1,0]
	v_pk_mul_f32 v[74:75], v[74:75], v[226:227] op_sel_hi:[1,0]
	v_pk_mul_f32 v[76:77], v[76:77], v[226:227] op_sel_hi:[1,0]
	v_pk_mul_f32 v[78:79], v[78:79], v[226:227] op_sel_hi:[1,0]
	v_pk_mul_f32 v[80:81], v[80:81], v[226:227] op_sel_hi:[1,0]
	s_nop 1
